# layer 0 after the out->norm barrier: half of each XCD's workgroups run the latency-bound weight re-conversion before their bandwidth-bound norm part-2 stores (order mixing)
# speedup vs baseline: 1.0096x; 1.0096x over previous
.LBB0_177:
	s_or_b64 exec, exec, s[0:1]
	v_readlane_b32 s0, v252, 23
	s_nop 3
	s_cmp_eq_u32 s0, 0
	s_cbranch_scc1 .Lfz_l1
	s_bitcmp1_b32 s52, 3
	s_cbranch_scc0 .Lfz_p2
	s_mov_b32 s32, 5
	v_mov_b32_e32 v184, v20
	v_mov_b32_e32 v185, v21
	s_mov_b32 s2, s96
	s_mov_b32 s3, s97
	s_branch .LBB0_771
.Lfz_p2:
	s_cmp_eq_u32 s32, 5
	s_cbranch_scc0 .Lfz_p2n
	v_mov_b32_e32 v20, v184
	v_mov_b32_e32 v21, v185
.Lfz_p2n:
	s_barrier
	s_add_u32 s44, s96, 0x6000000
	s_addc_u32 s45, s97, 0
	v_lshlrev_b32_e32 v158, 4, v148
	global_load_dwordx4 v[0:3], v158, s[44:45] offset:0
	global_load_dwordx4 v[4:7], v158, s[44:45] offset:256
	global_load_dwordx4 v[8:11], v158, s[44:45] offset:512
	global_load_dwordx4 v[12:15], v158, s[44:45] offset:768
	global_load_dwordx4 v[16:19], v158, s[44:45] offset:2048
	global_load_dwordx4 v[120:123], v158, s[44:45] offset:2304
	global_load_dwordx4 v[124:127], v158, s[44:45] offset:2560
	global_load_dwordx4 v[154:157], v158, s[44:45] offset:2816
	v_mov_b32_e32 v159, 0x358637bd
	s_mov_b32 s42, 0x800000
	s_waitcnt vmcnt(0)
	v_add_f32_e32 v0, v0, v1
	v_add_f32_e32 v0, v0, v2
	v_add_f32_e32 v0, v0, v3
	v_fmamk_f32 v0, v0, 0x3a800000, v159
	v_mul_f32_e32 v1, 0x4b800000, v0
	v_cmp_gt_f32_e32 vcc, s42, v0
	s_nop 1
	v_cndmask_b32_e32 v0, v0, v1, vcc
	v_rsq_f32_e32 v0, v0
	s_nop 0
	v_mul_f32_e32 v1, 0x45800000, v0
	v_cndmask_b32_e32 v184, v0, v1, vcc
	v_add_f32_e32 v4, v4, v5
	v_add_f32_e32 v4, v4, v6
	v_add_f32_e32 v4, v4, v7
	v_fmamk_f32 v4, v4, 0x3a800000, v159
	v_mul_f32_e32 v5, 0x4b800000, v4
	v_cmp_gt_f32_e32 vcc, s42, v4
	s_nop 1
	v_cndmask_b32_e32 v4, v4, v5, vcc
	v_rsq_f32_e32 v4, v4
	s_nop 0
	v_mul_f32_e32 v5, 0x45800000, v4
	v_cndmask_b32_e32 v186, v4, v5, vcc
	v_add_f32_e32 v8, v8, v9
	v_add_f32_e32 v8, v8, v10
	v_add_f32_e32 v8, v8, v11
	v_fmamk_f32 v8, v8, 0x3a800000, v159
	v_mul_f32_e32 v9, 0x4b800000, v8
	v_cmp_gt_f32_e32 vcc, s42, v8
	s_nop 1
	v_cndmask_b32_e32 v8, v8, v9, vcc
	v_rsq_f32_e32 v8, v8
	s_nop 0
	v_mul_f32_e32 v9, 0x45800000, v8
	v_cndmask_b32_e32 v188, v8, v9, vcc
	v_add_f32_e32 v12, v12, v13
	v_add_f32_e32 v12, v12, v14
	v_add_f32_e32 v12, v12, v15
	v_fmamk_f32 v12, v12, 0x3a800000, v159
	v_mul_f32_e32 v13, 0x4b800000, v12
	v_cmp_gt_f32_e32 vcc, s42, v12
	s_nop 1
	v_cndmask_b32_e32 v12, v12, v13, vcc
	v_rsq_f32_e32 v12, v12
	s_nop 0
	v_mul_f32_e32 v13, 0x45800000, v12
	v_cndmask_b32_e32 v190, v12, v13, vcc
	v_add_f32_e32 v16, v16, v17
	v_add_f32_e32 v16, v16, v18
	v_add_f32_e32 v16, v16, v19
	v_fmamk_f32 v16, v16, 0x3a800000, v159
	v_mul_f32_e32 v17, 0x4b800000, v16
	v_cmp_gt_f32_e32 vcc, s42, v16
	s_nop 1
	v_cndmask_b32_e32 v16, v16, v17, vcc
	v_rsq_f32_e32 v16, v16
	s_nop 0
	v_mul_f32_e32 v17, 0x45800000, v16
	v_cndmask_b32_e32 v16, v16, v17, vcc
	v_add_f32_e32 v120, v120, v121
	v_add_f32_e32 v120, v120, v122
	v_add_f32_e32 v120, v120, v123
	v_fmamk_f32 v120, v120, 0x3a800000, v159
	v_mul_f32_e32 v121, 0x4b800000, v120
	v_cmp_gt_f32_e32 vcc, s42, v120
	s_nop 1
	v_cndmask_b32_e32 v120, v120, v121, vcc
	v_rsq_f32_e32 v120, v120
	s_nop 0
	v_mul_f32_e32 v121, 0x45800000, v120
	v_cndmask_b32_e32 v18, v120, v121, vcc
	v_add_f32_e32 v124, v124, v125
	v_add_f32_e32 v124, v124, v126
	v_add_f32_e32 v124, v124, v127
	v_fmamk_f32 v124, v124, 0x3a800000, v159
	v_mul_f32_e32 v125, 0x4b800000, v124
	v_cmp_gt_f32_e32 vcc, s42, v124
	s_nop 1
	v_cndmask_b32_e32 v124, v124, v125, vcc
	v_rsq_f32_e32 v124, v124
	s_nop 0
	v_mul_f32_e32 v125, 0x45800000, v124
	v_cndmask_b32_e32 v142, v124, v125, vcc
	v_add_f32_e32 v154, v154, v155
	v_add_f32_e32 v154, v154, v156
	v_add_f32_e32 v154, v154, v157
	v_fmamk_f32 v154, v154, 0x3a800000, v159
	v_mul_f32_e32 v155, 0x4b800000, v154
	v_cmp_gt_f32_e32 vcc, s42, v154
	s_nop 1
	v_cndmask_b32_e32 v154, v154, v155, vcc
	v_rsq_f32_e32 v154, v154
	s_nop 0
	v_mul_f32_e32 v155, 0x45800000, v154
	v_cndmask_b32_e32 v144, v154, v155, vcc
	v_readlane_b32 s0, v253, 14
	v_readlane_b32 s1, v253, 15
	s_nop 3
	s_add_u32 s0, s0, 0x1000
	s_addc_u32 s1, s1, 0
	v_lshl_add_u64 v[160:161], s[0:1], 0, v[146:147]
	v_lshrrev_b32_e32 v216, 12, v148
	v_mul_u32_u24_e32 v216, 0x3000, v216
	v_mov_b32_e32 v217, 0
	s_add_u32 s0, s96, 0x10acc000
	s_addc_u32 s1, s97, 0
	v_lshl_add_u64 v[216:217], s[0:1], 0, v[216:217]
	v_lshl_add_u64 v[216:217], v[216:217], 0, v[146:147]
	s_mov_b64 s[0:1], 0x1000
	v_lshl_add_u64 v[192:193], v[216:217], 0, s[0:1]
	global_load_dwordx4 v[0:3], v[160:161], off offset:16
	global_load_dwordx4 v[4:7], v[160:161], off offset:0
	global_load_dwordx4 v[8:11], v[160:161], off offset:528
	global_load_dwordx4 v[12:15], v[160:161], off offset:512
	global_load_dwordx4 v[236:239], v[192:193], off offset:16
	global_load_dwordx4 v[240:243], v[192:193], off offset:0
	global_load_dwordx4 v[244:247], v[192:193], off offset:528
	global_load_dwordx4 v[248:251], v[192:193], off offset:512
	global_load_dwordx4 v[120:123], v[216:217], off offset:16
	global_load_dwordx4 v[124:127], v[216:217], off offset:0
	global_load_dwordx4 v[154:157], v[216:217], off offset:528
	global_load_dwordx4 v[158:161], v[216:217], off offset:512
	v_lshlrev_b32_e32 v162, 12, v148
	v_mov_b32_e32 v163, 0
	v_lshl_add_u64 v[162:163], s[94:95], 0, v[162:163]
	v_lshl_add_u64 v[162:163], v[162:163], 0, v[146:147]
	v_lshlrev_b32_e32 v140, 11, v148
	v_lshrrev_b32_e32 v141, 1, v146
	v_add_u32_e32 v140, v140, v141
	v_mov_b32_e32 v141, 0
	s_add_u32 s0, s96, 0xb000000
	s_addc_u32 s1, s97, 0
	v_lshl_add_u64 v[140:141], s[0:1], 0, v[140:141]
	s_waitcnt vmcnt(4)
	v_pk_fma_f32 v[0:1], v[0:1], v[236:237], v[0:1]
	v_pk_fma_f32 v[2:3], v[2:3], v[238:239], v[2:3]
	v_pk_fma_f32 v[4:5], v[4:5], v[240:241], v[4:5]
	v_pk_fma_f32 v[6:7], v[6:7], v[242:243], v[6:7]
	v_pk_fma_f32 v[8:9], v[8:9], v[244:245], v[8:9]
	v_pk_fma_f32 v[10:11], v[10:11], v[246:247], v[10:11]
	v_pk_fma_f32 v[12:13], v[12:13], v[248:249], v[12:13]
	v_pk_fma_f32 v[14:15], v[14:15], v[250:251], v[14:15]
	s_waitcnt vmcnt(0)
	global_store_dwordx4 v[162:163], v[128:131], off offset:16
	global_store_dwordx4 v[162:163], v[132:135], off offset:0
	v_pk_mul_f32 v[236:237], v[132:133], v[184:185] op_sel_hi:[1,0]
	v_pk_mul_f32 v[238:239], v[134:135], v[184:185] op_sel_hi:[1,0]
	v_pk_fma_f32 v[236:237], v[236:237], v[4:5], v[124:125]
	v_pk_fma_f32 v[238:239], v[238:239], v[6:7], v[126:127]
	v_cvt_pk_bf16_f32 v244, v236, v237
	v_cvt_pk_bf16_f32 v245, v238, v239
	v_pk_mul_f32 v[236:237], v[128:129], v[184:185] op_sel_hi:[1,0]
	v_pk_mul_f32 v[238:239], v[130:131], v[184:185] op_sel_hi:[1,0]
	v_pk_fma_f32 v[236:237], v[236:237], v[0:1], v[120:121]
	v_pk_fma_f32 v[238:239], v[238:239], v[2:3], v[122:123]
	v_cvt_pk_bf16_f32 v246, v236, v237
	v_cvt_pk_bf16_f32 v247, v238, v239
	global_store_dwordx4 v[140:141], v[244:247], off offset:0
	global_store_dwordx4 v[162:163], v[56:59], off offset:528
	global_store_dwordx4 v[162:163], v[64:67], off offset:512
	v_pk_mul_f32 v[236:237], v[64:65], v[184:185] op_sel_hi:[1,0]
	v_pk_mul_f32 v[238:239], v[66:67], v[184:185] op_sel_hi:[1,0]
	v_pk_fma_f32 v[236:237], v[236:237], v[12:13], v[158:159]
	v_pk_fma_f32 v[238:239], v[238:239], v[14:15], v[160:161]
	v_cvt_pk_bf16_f32 v248, v236, v237
	v_cvt_pk_bf16_f32 v249, v238, v239
	v_pk_mul_f32 v[236:237], v[56:57], v[184:185] op_sel_hi:[1,0]
	v_pk_mul_f32 v[238:239], v[58:59], v[184:185] op_sel_hi:[1,0]
	v_pk_fma_f32 v[236:237], v[236:237], v[8:9], v[154:155]
	v_pk_fma_f32 v[238:239], v[238:239], v[10:11], v[156:157]
	v_cvt_pk_bf16_f32 v250, v236, v237
	v_cvt_pk_bf16_f32 v251, v238, v239
	global_store_dwordx4 v[140:141], v[248:251], off offset:256
	s_mov_b64 s[0:1], 0x10000
	v_lshl_add_u64 v[212:213], v[162:163], 0, s[0:1]
	s_mov_b64 s[0:1], 0x8000
	v_lshl_add_u64 v[136:137], v[140:141], 0, s[0:1]
	global_store_dwordx4 v[212:213], v[112:115], off offset:16
	global_store_dwordx4 v[212:213], v[116:119], off offset:0
	v_pk_mul_f32 v[236:237], v[116:117], v[186:187] op_sel_hi:[1,0]
	v_pk_mul_f32 v[238:239], v[118:119], v[186:187] op_sel_hi:[1,0]
	v_pk_fma_f32 v[236:237], v[236:237], v[4:5], v[124:125]
	v_pk_fma_f32 v[238:239], v[238:239], v[6:7], v[126:127]
	v_cvt_pk_bf16_f32 v244, v236, v237
	v_cvt_pk_bf16_f32 v245, v238, v239
	v_pk_mul_f32 v[236:237], v[112:113], v[186:187] op_sel_hi:[1,0]
	v_pk_mul_f32 v[238:239], v[114:115], v[186:187] op_sel_hi:[1,0]
	v_pk_fma_f32 v[236:237], v[236:237], v[0:1], v[120:121]
	v_pk_fma_f32 v[238:239], v[238:239], v[2:3], v[122:123]
	v_cvt_pk_bf16_f32 v246, v236, v237
	v_cvt_pk_bf16_f32 v247, v238, v239
	global_store_dwordx4 v[136:137], v[244:247], off offset:0
	global_store_dwordx4 v[212:213], v[48:51], off offset:528
	global_store_dwordx4 v[212:213], v[52:55], off offset:512
	v_pk_mul_f32 v[236:237], v[52:53], v[186:187] op_sel_hi:[1,0]
	v_pk_mul_f32 v[238:239], v[54:55], v[186:187] op_sel_hi:[1,0]
	v_pk_fma_f32 v[236:237], v[236:237], v[12:13], v[158:159]
	v_pk_fma_f32 v[238:239], v[238:239], v[14:15], v[160:161]
	v_cvt_pk_bf16_f32 v248, v236, v237
	v_cvt_pk_bf16_f32 v249, v238, v239
	v_pk_mul_f32 v[236:237], v[48:49], v[186:187] op_sel_hi:[1,0]
	v_pk_mul_f32 v[238:239], v[50:51], v[186:187] op_sel_hi:[1,0]
	v_pk_fma_f32 v[236:237], v[236:237], v[8:9], v[154:155]
	v_pk_fma_f32 v[238:239], v[238:239], v[10:11], v[156:157]
	v_cvt_pk_bf16_f32 v250, v236, v237
	v_cvt_pk_bf16_f32 v251, v238, v239
	global_store_dwordx4 v[136:137], v[248:251], off offset:256
	s_mov_b64 s[0:1], 0x20000
	v_lshl_add_u64 v[214:215], v[162:163], 0, s[0:1]
	s_mov_b64 s[0:1], 0x10000
	v_lshl_add_u64 v[138:139], v[140:141], 0, s[0:1]
	global_store_dwordx4 v[214:215], v[104:107], off offset:16
	global_store_dwordx4 v[214:215], v[108:111], off offset:0
	v_pk_mul_f32 v[236:237], v[108:109], v[188:189] op_sel_hi:[1,0]
	v_pk_mul_f32 v[238:239], v[110:111], v[188:189] op_sel_hi:[1,0]
	v_pk_fma_f32 v[236:237], v[236:237], v[4:5], v[124:125]
	v_pk_fma_f32 v[238:239], v[238:239], v[6:7], v[126:127]
	v_cvt_pk_bf16_f32 v244, v236, v237
	v_cvt_pk_bf16_f32 v245, v238, v239
	v_pk_mul_f32 v[236:237], v[104:105], v[188:189] op_sel_hi:[1,0]
	v_pk_mul_f32 v[238:239], v[106:107], v[188:189] op_sel_hi:[1,0]
	v_pk_fma_f32 v[236:237], v[236:237], v[0:1], v[120:121]
	v_pk_fma_f32 v[238:239], v[238:239], v[2:3], v[122:123]
	v_cvt_pk_bf16_f32 v246, v236, v237
	v_cvt_pk_bf16_f32 v247, v238, v239
	global_store_dwordx4 v[138:139], v[244:247], off offset:0
	global_store_dwordx4 v[214:215], v[40:43], off offset:528
	global_store_dwordx4 v[214:215], v[44:47], off offset:512
	v_pk_mul_f32 v[236:237], v[44:45], v[188:189] op_sel_hi:[1,0]
	v_pk_mul_f32 v[238:239], v[46:47], v[188:189] op_sel_hi:[1,0]
	v_pk_fma_f32 v[236:237], v[236:237], v[12:13], v[158:159]
	v_pk_fma_f32 v[238:239], v[238:239], v[14:15], v[160:161]
	v_cvt_pk_bf16_f32 v248, v236, v237
	v_cvt_pk_bf16_f32 v249, v238, v239
	v_pk_mul_f32 v[236:237], v[40:41], v[188:189] op_sel_hi:[1,0]
	v_pk_mul_f32 v[238:239], v[42:43], v[188:189] op_sel_hi:[1,0]
	v_pk_fma_f32 v[236:237], v[236:237], v[8:9], v[154:155]
	v_pk_fma_f32 v[238:239], v[238:239], v[10:11], v[156:157]
	v_cvt_pk_bf16_f32 v250, v236, v237
	v_cvt_pk_bf16_f32 v251, v238, v239
	global_store_dwordx4 v[138:139], v[248:251], off offset:256
	s_mov_b64 s[0:1], 0x30000
	v_lshl_add_u64 v[212:213], v[162:163], 0, s[0:1]
	s_mov_b64 s[0:1], 0x18000
	v_lshl_add_u64 v[136:137], v[140:141], 0, s[0:1]
	global_store_dwordx4 v[212:213], v[96:99], off offset:16
	global_store_dwordx4 v[212:213], v[100:103], off offset:0
	v_pk_mul_f32 v[236:237], v[100:101], v[190:191] op_sel_hi:[1,0]
	v_pk_mul_f32 v[238:239], v[102:103], v[190:191] op_sel_hi:[1,0]
	v_pk_fma_f32 v[236:237], v[236:237], v[4:5], v[124:125]
	v_pk_fma_f32 v[238:239], v[238:239], v[6:7], v[126:127]
	v_cvt_pk_bf16_f32 v244, v236, v237
	v_cvt_pk_bf16_f32 v245, v238, v239
	v_pk_mul_f32 v[236:237], v[96:97], v[190:191] op_sel_hi:[1,0]
	v_pk_mul_f32 v[238:239], v[98:99], v[190:191] op_sel_hi:[1,0]
	v_pk_fma_f32 v[236:237], v[236:237], v[0:1], v[120:121]
	v_pk_fma_f32 v[238:239], v[238:239], v[2:3], v[122:123]
	v_cvt_pk_bf16_f32 v246, v236, v237
	v_cvt_pk_bf16_f32 v247, v238, v239
	global_store_dwordx4 v[136:137], v[244:247], off offset:0
	global_store_dwordx4 v[212:213], v[32:35], off offset:528
	global_store_dwordx4 v[212:213], v[36:39], off offset:512
	v_pk_mul_f32 v[236:237], v[36:37], v[190:191] op_sel_hi:[1,0]
	v_pk_mul_f32 v[238:239], v[38:39], v[190:191] op_sel_hi:[1,0]
	v_pk_fma_f32 v[236:237], v[236:237], v[12:13], v[158:159]
	v_pk_fma_f32 v[238:239], v[238:239], v[14:15], v[160:161]
	v_cvt_pk_bf16_f32 v248, v236, v237
	v_cvt_pk_bf16_f32 v249, v238, v239
	v_pk_mul_f32 v[236:237], v[32:33], v[190:191] op_sel_hi:[1,0]
	v_pk_mul_f32 v[238:239], v[34:35], v[190:191] op_sel_hi:[1,0]
	v_pk_fma_f32 v[236:237], v[236:237], v[8:9], v[154:155]
	v_pk_fma_f32 v[238:239], v[238:239], v[10:11], v[156:157]
	v_cvt_pk_bf16_f32 v250, v236, v237
	v_cvt_pk_bf16_f32 v251, v238, v239
	global_store_dwordx4 v[136:137], v[248:251], off offset:256
	s_mov_b64 s[0:1], 0x80000
	v_lshl_add_u64 v[214:215], v[162:163], 0, s[0:1]
	s_mov_b64 s[0:1], 0x40000
	v_lshl_add_u64 v[138:139], v[140:141], 0, s[0:1]
	global_store_dwordx4 v[214:215], v[88:91], off offset:16
	global_store_dwordx4 v[214:215], v[92:95], off offset:0
	v_pk_mul_f32 v[236:237], v[92:93], v[16:17] op_sel_hi:[1,0]
	v_pk_mul_f32 v[238:239], v[94:95], v[16:17] op_sel_hi:[1,0]
	v_pk_fma_f32 v[236:237], v[236:237], v[4:5], v[124:125]
	v_pk_fma_f32 v[238:239], v[238:239], v[6:7], v[126:127]
	v_cvt_pk_bf16_f32 v244, v236, v237
	v_cvt_pk_bf16_f32 v245, v238, v239
	v_pk_mul_f32 v[236:237], v[88:89], v[16:17] op_sel_hi:[1,0]
	v_pk_mul_f32 v[238:239], v[90:91], v[16:17] op_sel_hi:[1,0]
	v_pk_fma_f32 v[236:237], v[236:237], v[0:1], v[120:121]
	v_pk_fma_f32 v[238:239], v[238:239], v[2:3], v[122:123]
	v_cvt_pk_bf16_f32 v246, v236, v237
	v_cvt_pk_bf16_f32 v247, v238, v239
	global_store_dwordx4 v[138:139], v[244:247], off offset:0
	global_store_dwordx4 v[214:215], v[24:27], off offset:528
	global_store_dwordx4 v[214:215], v[28:31], off offset:512
	v_pk_mul_f32 v[236:237], v[28:29], v[16:17] op_sel_hi:[1,0]
	v_pk_mul_f32 v[238:239], v[30:31], v[16:17] op_sel_hi:[1,0]
	v_pk_fma_f32 v[236:237], v[236:237], v[12:13], v[158:159]
	v_pk_fma_f32 v[238:239], v[238:239], v[14:15], v[160:161]
	v_cvt_pk_bf16_f32 v248, v236, v237
	v_cvt_pk_bf16_f32 v249, v238, v239
	v_pk_mul_f32 v[236:237], v[24:25], v[16:17] op_sel_hi:[1,0]
	v_pk_mul_f32 v[238:239], v[26:27], v[16:17] op_sel_hi:[1,0]
	v_pk_fma_f32 v[236:237], v[236:237], v[8:9], v[154:155]
	v_pk_fma_f32 v[238:239], v[238:239], v[10:11], v[156:157]
	v_cvt_pk_bf16_f32 v250, v236, v237
	v_cvt_pk_bf16_f32 v251, v238, v239
	global_store_dwordx4 v[138:139], v[248:251], off offset:256
	s_mov_b64 s[0:1], 0x90000
	v_lshl_add_u64 v[212:213], v[162:163], 0, s[0:1]
	s_mov_b64 s[0:1], 0x48000
	v_lshl_add_u64 v[136:137], v[140:141], 0, s[0:1]
	global_store_dwordx4 v[212:213], v[80:83], off offset:16
	global_store_dwordx4 v[212:213], v[84:87], off offset:0
	v_pk_mul_f32 v[236:237], v[84:85], v[18:19] op_sel_hi:[1,0]
	v_pk_mul_f32 v[238:239], v[86:87], v[18:19] op_sel_hi:[1,0]
	v_pk_fma_f32 v[236:237], v[236:237], v[4:5], v[124:125]
	v_pk_fma_f32 v[238:239], v[238:239], v[6:7], v[126:127]
	v_cvt_pk_bf16_f32 v244, v236, v237
	v_cvt_pk_bf16_f32 v245, v238, v239
	v_pk_mul_f32 v[236:237], v[80:81], v[18:19] op_sel_hi:[1,0]
	v_pk_mul_f32 v[238:239], v[82:83], v[18:19] op_sel_hi:[1,0]
	v_pk_fma_f32 v[236:237], v[236:237], v[0:1], v[120:121]
	v_pk_fma_f32 v[238:239], v[238:239], v[2:3], v[122:123]
	v_cvt_pk_bf16_f32 v246, v236, v237
	v_cvt_pk_bf16_f32 v247, v238, v239
	global_store_dwordx4 v[136:137], v[244:247], off offset:0
	global_store_dwordx4 v[212:213], v[180:183], off offset:528
	global_store_dwordx4 v[212:213], v[20:23], off offset:512
	v_pk_mul_f32 v[236:237], v[20:21], v[18:19] op_sel_hi:[1,0]
	v_pk_mul_f32 v[238:239], v[22:23], v[18:19] op_sel_hi:[1,0]
	v_pk_fma_f32 v[236:237], v[236:237], v[12:13], v[158:159]
	v_pk_fma_f32 v[238:239], v[238:239], v[14:15], v[160:161]
	v_cvt_pk_bf16_f32 v248, v236, v237
	v_cvt_pk_bf16_f32 v249, v238, v239
	v_pk_mul_f32 v[236:237], v[180:181], v[18:19] op_sel_hi:[1,0]
	v_pk_mul_f32 v[238:239], v[182:183], v[18:19] op_sel_hi:[1,0]
	v_pk_fma_f32 v[236:237], v[236:237], v[8:9], v[154:155]
	v_pk_fma_f32 v[238:239], v[238:239], v[10:11], v[156:157]
	v_cvt_pk_bf16_f32 v250, v236, v237
	v_cvt_pk_bf16_f32 v251, v238, v239
	global_store_dwordx4 v[136:137], v[248:251], off offset:256
	s_mov_b64 s[0:1], 0xa0000
	v_lshl_add_u64 v[214:215], v[162:163], 0, s[0:1]
	s_mov_b64 s[0:1], 0x50000
	v_lshl_add_u64 v[138:139], v[140:141], 0, s[0:1]
	global_store_dwordx4 v[214:215], v[72:75], off offset:16
	global_store_dwordx4 v[214:215], v[76:79], off offset:0
	v_pk_mul_f32 v[236:237], v[76:77], v[142:143] op_sel_hi:[1,0]
	v_pk_mul_f32 v[238:239], v[78:79], v[142:143] op_sel_hi:[1,0]
	v_pk_fma_f32 v[236:237], v[236:237], v[4:5], v[124:125]
	v_pk_fma_f32 v[238:239], v[238:239], v[6:7], v[126:127]
	v_cvt_pk_bf16_f32 v244, v236, v237
	v_cvt_pk_bf16_f32 v245, v238, v239
	v_pk_mul_f32 v[236:237], v[72:73], v[142:143] op_sel_hi:[1,0]
	v_pk_mul_f32 v[238:239], v[74:75], v[142:143] op_sel_hi:[1,0]
	v_pk_fma_f32 v[236:237], v[236:237], v[0:1], v[120:121]
	v_pk_fma_f32 v[238:239], v[238:239], v[2:3], v[122:123]
	v_cvt_pk_bf16_f32 v246, v236, v237
	v_cvt_pk_bf16_f32 v247, v238, v239
	global_store_dwordx4 v[138:139], v[244:247], off offset:0
	global_store_dwordx4 v[214:215], v[172:175], off offset:528
	global_store_dwordx4 v[214:215], v[176:179], off offset:512
	v_pk_mul_f32 v[236:237], v[176:177], v[142:143] op_sel_hi:[1,0]
	v_pk_mul_f32 v[238:239], v[178:179], v[142:143] op_sel_hi:[1,0]
	v_pk_fma_f32 v[236:237], v[236:237], v[12:13], v[158:159]
	v_pk_fma_f32 v[238:239], v[238:239], v[14:15], v[160:161]
	v_cvt_pk_bf16_f32 v248, v236, v237
	v_cvt_pk_bf16_f32 v249, v238, v239
	v_pk_mul_f32 v[236:237], v[172:173], v[142:143] op_sel_hi:[1,0]
	v_pk_mul_f32 v[238:239], v[174:175], v[142:143] op_sel_hi:[1,0]
	v_pk_fma_f32 v[236:237], v[236:237], v[8:9], v[154:155]
	v_pk_fma_f32 v[238:239], v[238:239], v[10:11], v[156:157]
	v_cvt_pk_bf16_f32 v250, v236, v237
	v_cvt_pk_bf16_f32 v251, v238, v239
	global_store_dwordx4 v[138:139], v[248:251], off offset:256
	s_mov_b64 s[0:1], 0xb0000
	v_lshl_add_u64 v[212:213], v[162:163], 0, s[0:1]
	s_mov_b64 s[0:1], 0x58000
	v_lshl_add_u64 v[136:137], v[140:141], 0, s[0:1]
	global_store_dwordx4 v[212:213], v[60:63], off offset:16
	global_store_dwordx4 v[212:213], v[68:71], off offset:0
	v_pk_mul_f32 v[236:237], v[68:69], v[144:145] op_sel_hi:[1,0]
	v_pk_mul_f32 v[238:239], v[70:71], v[144:145] op_sel_hi:[1,0]
	v_pk_fma_f32 v[236:237], v[236:237], v[4:5], v[124:125]
	v_pk_fma_f32 v[238:239], v[238:239], v[6:7], v[126:127]
	v_cvt_pk_bf16_f32 v244, v236, v237
	v_cvt_pk_bf16_f32 v245, v238, v239
	v_pk_mul_f32 v[236:237], v[60:61], v[144:145] op_sel_hi:[1,0]
	v_pk_mul_f32 v[238:239], v[62:63], v[144:145] op_sel_hi:[1,0]
	v_pk_fma_f32 v[236:237], v[236:237], v[0:1], v[120:121]
	v_pk_fma_f32 v[238:239], v[238:239], v[2:3], v[122:123]
	v_cvt_pk_bf16_f32 v246, v236, v237
	v_cvt_pk_bf16_f32 v247, v238, v239
	global_store_dwordx4 v[136:137], v[244:247], off offset:0
	global_store_dwordx4 v[212:213], v[164:167], off offset:528
	global_store_dwordx4 v[212:213], v[168:171], off offset:512
	v_pk_mul_f32 v[236:237], v[168:169], v[144:145] op_sel_hi:[1,0]
	v_pk_mul_f32 v[238:239], v[170:171], v[144:145] op_sel_hi:[1,0]
	v_pk_fma_f32 v[236:237], v[236:237], v[12:13], v[158:159]
	v_pk_fma_f32 v[238:239], v[238:239], v[14:15], v[160:161]
	v_cvt_pk_bf16_f32 v248, v236, v237
	v_cvt_pk_bf16_f32 v249, v238, v239
	v_pk_mul_f32 v[236:237], v[164:165], v[144:145] op_sel_hi:[1,0]
	v_pk_mul_f32 v[238:239], v[166:167], v[144:145] op_sel_hi:[1,0]
	v_pk_fma_f32 v[236:237], v[236:237], v[8:9], v[154:155]
	v_pk_fma_f32 v[238:239], v[238:239], v[10:11], v[156:157]
	v_cvt_pk_bf16_f32 v250, v236, v237
	v_cvt_pk_bf16_f32 v251, v238, v239
	global_store_dwordx4 v[136:137], v[248:251], off offset:256
	s_cmp_eq_u32 s32, 5
	s_cbranch_scc1 .Lcvt_ret

.LBB0_771:
	v_readlane_b32 s0, v252, 23
	v_readlane_b32 s1, v252, 24
	s_andn2_b64 vcc, exec, s[0:1]
	s_waitcnt lgkmcnt(0)
	s_barrier
	s_cmp_eq_u32 s32, 3
	s_cbranch_scc1 .Lp2q_go
	s_cmp_lg_u32 s32, 5
	s_cbranch_scc1 .LBB0_808
.Lp2q_go:
	s_cbranch_vccnz .LBB0_808
	v_readlane_b32 s0, v253, 48
	v_readlane_b32 s1, v253, 49
	v_mov_b32_e32 v8, v197
	s_andn2_b64 vcc, exec, s[0:1]
	s_cbranch_vccnz .LBB0_808
	v_readlane_b32 s0, v253, 59
	v_ashrrev_i32_e32 v12, 4, v8
	v_lshlrev_b32_e32 v0, 2, v8
	v_readlane_b32 s4, v253, 52
	v_readlane_b32 s1, v253, 60
	v_and_b32_e32 v10, 60, v0
	v_add_u32_e32 v2, s4, v12
	v_mov_b64_e32 v[0:1], s[0:1]
	s_mov_b32 s5, 0x8800
	v_mad_i64_i32 v[2:3], s[0:1], v2, s5, v[0:1]
	v_readlane_b32 s0, v253, 53
	v_lshlrev_b32_e32 v194, 2, v10
	v_lshl_add_u64 v[2:3], v[2:3], 0, v[194:195]
	v_add_u32_e32 v4, s0, v12
	v_mad_i64_i32 v[0:1], s[0:1], v4, s5, v[0:1]
	v_lshl_add_u64 v[4:5], v[0:1], 0, v[194:195]
	global_load_dwordx4 v[0:3], v[2:3], off
	s_nop 0
	global_load_dwordx4 v[4:7], v[4:5], off
	s_add_u32 s0, s2, 0xf000000
	s_movk_i32 s2, 0x104
	v_ashrrev_i32_e32 v14, 3, v8
	v_lshlrev_b32_e32 v8, 3, v8
	v_mul_lo_u32 v9, v12, s2
	v_and_b32_e32 v16, 56, v8
	v_readlane_b32 s6, v253, 55
	s_addc_u32 s1, s3, 0
	v_add3_u32 v13, 0, v9, v194
	v_mad_u32_u24 v15, v16, s2, 0
	v_lshlrev_b32_e32 v8, 2, v10
	v_lshlrev_b32_e32 v194, 1, v16
	v_readlane_b32 s2, v252, 0
	v_readlane_b32 s3, v253, 63
	v_readlane_b32 s10, v253, 50
	s_mov_b32 s5, s6
	s_mov_b32 s23, s52
	v_readlane_b32 s7, v253, 56
	s_branch .LBB0_775

.LBB0_808:
	s_cmp_eq_u32 s32, 3
	s_cbranch_scc1 .Lcvt_ret
	s_cmp_eq_u32 s32, 5
	s_cbranch_scc1 .Lfz_p2
	s_waitcnt vmcnt(0)
	s_barrier
	s_and_saveexec_b64 s[0:1], s[54:55]
	s_cbranch_execz .LBB0_177
	s_mov_b32 s2, s53
	s_mov_b64 s[4:5], 0
	s_waitcnt vmcnt(2)
	v_mov_b32_e32 v0, s73
	s_waitcnt vmcnt(0) expcnt(0) lgkmcnt(0)
	ds_read_b32 v2, v0
	v_mov_b32_e32 v0, s74
	ds_read_b32 v0, v0
	s_lshl_b64 s[4:5], s[4:5], 2
	v_readlane_b32 s6, v253, 24
	v_readlane_b32 s7, v253, 25
	s_add_u32 s4, s6, s4
	s_waitcnt lgkmcnt(1)
	v_cmp_ne_u32_e32 vcc, 0, v2
	s_addc_u32 s5, s7, s5
	s_cbranch_vccnz .LBB0_824
	s_add_u32 s6, s4, 0x1000
	s_addc_u32 s7, s5, 0
	s_add_u32 s8, s4, 0x1100
	s_addc_u32 s9, s5, 0
	s_add_u32 s10, s4, 0x1200
	s_addc_u32 s11, s5, 0
	s_add_u32 s12, s4, 0x1300
	s_addc_u32 s13, s5, 0
	s_mov_b32 s3, 1
	s_branch .LBB0_812
